# attention next-tile loads spread through QK MFMA chain + SSD sb-loop prefetch + EpiKV hoist
# speedup vs baseline: 1.0028x; 1.0028x over previous
; #define LAS __attribute__((address_space(3)))
; #define MFMA32(a, b, c) __builtin_amdgcn_mfma_f32_32x32x16_bf16((a), (b), (c), 0, 0, 0)
; __device__ __forceinline__ void attn_item(LAS unsigned char* lds, int b, int h, int qb, const bf16_t* Q, const bf16_t* KN, const bf16_t* KR, const bf16_t* VT, bf16_t* MIXIN, float* STAT2) {
;     ...
;     for (int j = 0; j < NT; ++j) {
;         const int vnext = (vcur == 2) ? 0 : vcur + 1;
;         if (j + 1 < NT) AT_LOAD(j + 1);
;         const int jb = j - (NT - 4);
;         if (!(jb >= 0 && 64 * jb > 32 * w + 31)) {
;             f32x16 p0, p1;
; #pragma unroll
;             for (int r = 0; r < 16; ++r) { p0[r] = 0.f; p1[r] = 0.f; }
;             const LAS unsigned char* kbase = lds + (j & 1) * KB + c * KP + hi * 16;
;             {
;     ...
;                 bf16x8 kb0 = AT_KLD(0), kb1 = AT_KLD(1), kb2 = AT_KLD(2);
; #pragma unroll
;                 for (int i = 0; i < 24; ++i) {
;                     const bf16x8 cur = (i % 3 == 0) ? kb0 : ((i % 3 == 1) ? kb1 : kb2);
;                     if (i & 1) p1 = MFMA32(cur, qf[i >> 1], p1); else p0 = MFMA32(cur, qf[i >> 1], p0);
;                     if (i + 3 < 24) { if (i % 3 == 0) kb0 = AT_KLD(i + 3); else if (i % 3 == 1) kb1 = AT_KLD(i + 3); else kb2 = AT_KLD(i + 3); }
.LBB0_960:
	s_cmp_lt_u32 s44, s34
	s_cselect_b64 s[14:15], -1, 0
	s_cmp_ge_u32 s44, s34
	s_cbranch_scc1 .LBB0_962
	v_add_u32_e32 v8, s35, v212
	v_add_u32_e32 v2, 64, v8
	v_lshlrev_b64 v[6:7], 8, v[2:3]
	v_add_u32_e32 v2, 0x60, v8
	v_lshl_add_u64 v[234:235], v[208:209], 0, v[6:7]
	v_lshlrev_b64 v[8:9], 8, v[2:3]
	v_add_u32_e32 v2, s35, v221
	s_add_i32 s8, s35, 64
	v_lshl_add_u64 v[236:237], v[208:209], 0, v[8:9]
	v_lshlrev_b64 v[6:7], 7, v[2:3]
	v_lshl_add_u64 v[238:239], v[206:207], 0, v[6:7]
	s_lshl_b64 s[16:17], s[8:9], 1
	v_lshl_add_u64 v[240:241], v[204:205], 0, s[16:17]
	v_lshl_add_u64 v[242:243], v[210:211], 0, s[16:17]
.LBB0_962:
	s_add_i32 s8, s33, s44
	s_sub_i32 s8, s8, 61
	s_cmp_gt_i32 s8, -1
	s_cselect_b64 s[16:17], -1, 0
	s_add_i32 s8, s31, s35
	s_addk_i32 s8, 0xf100
	s_cmp_gt_i32 s8, s30
	s_cselect_b64 s[46:47], -1, 0
	s_and_b64 s[46:47], s[16:17], s[46:47]
	s_and_b64 vcc, exec, s[46:47]
	s_cbranch_vccnz .Latt_skipld
	s_bitcmp1_b32 s44, 0
	s_cselect_b32 s8, 0, 0x6400
	v_add_u32_e32 v2, s8, v219
	ds_read_b128 v[6:9], v2
	ds_read_b128 v[10:13], v2 offset:32
	ds_read_b128 v[14:17], v2 offset:12800
	ds_read_b128 v[230:233], v2 offset:12832
	s_waitcnt lgkmcnt(3)
	v_mfma_f32_32x32x16_bf16 v[98:113], v[6:9], v[114:117], 0
	s_waitcnt lgkmcnt(1)
	v_mfma_f32_32x32x16_bf16 v[82:97], v[14:17], v[114:117], 0
	s_mov_b64 exec, s[14:15]
	global_load_dwordx4 v[138:141], v[234:235], off
	s_mov_b64 exec, -1
	ds_read_b128 v[6:9], v2 offset:64
	v_mfma_f32_32x32x16_bf16 v[98:113], v[10:13], v[118:121], v[98:113]
	ds_read_b128 v[14:17], v2 offset:12864
	s_waitcnt lgkmcnt(2)
	v_mfma_f32_32x32x16_bf16 v[82:97], v[230:233], v[118:121], v[82:97]
	ds_read_b128 v[10:13], v2 offset:96
	s_waitcnt lgkmcnt(2)
	v_mfma_f32_32x32x16_bf16 v[98:113], v[6:9], v[126:129], v[98:113]
	s_mov_b64 exec, s[14:15]
	global_load_dwordx4 v[122:125], v[236:237], off
	s_mov_b64 exec, -1
	ds_read_b128 v[230:233], v2 offset:12896
	s_waitcnt lgkmcnt(2)
	v_mfma_f32_32x32x16_bf16 v[82:97], v[14:17], v[126:129], v[82:97]
	ds_read_b128 v[6:9], v2 offset:128
	s_waitcnt lgkmcnt(2)
	v_mfma_f32_32x32x16_bf16 v[98:113], v[10:13], v[130:133], v[98:113]
	ds_read_b128 v[14:17], v2 offset:12928
	s_waitcnt lgkmcnt(2)
	v_mfma_f32_32x32x16_bf16 v[82:97], v[230:233], v[130:133], v[82:97]
	s_mov_b64 exec, s[14:15]
	global_load_dwordx4 v[170:173], v[238:239], off
	s_mov_b64 exec, -1
	ds_read_b128 v[10:13], v2 offset:160
	s_waitcnt lgkmcnt(2)
	v_mfma_f32_32x32x16_bf16 v[98:113], v[6:9], v[134:137], v[98:113]
	ds_read_b128 v[230:233], v2 offset:12960
	s_waitcnt lgkmcnt(2)
	v_mfma_f32_32x32x16_bf16 v[82:97], v[14:17], v[134:137], v[82:97]
	ds_read_b128 v[6:9], v2 offset:192
	s_waitcnt lgkmcnt(2)
	v_mfma_f32_32x32x16_bf16 v[98:113], v[10:13], v[142:145], v[98:113]
	s_mov_b64 exec, s[14:15]
	global_load_dwordx4 v[174:177], v[240:241], off
	s_mov_b64 exec, -1
	ds_read_b128 v[14:17], v2 offset:12992
	s_waitcnt lgkmcnt(2)
	v_mfma_f32_32x32x16_bf16 v[82:97], v[230:233], v[142:145], v[82:97]
	ds_read_b128 v[10:13], v2 offset:224
	s_waitcnt lgkmcnt(2)
	v_mfma_f32_32x32x16_bf16 v[98:113], v[6:9], v[146:149], v[98:113]
	ds_read_b128 v[230:233], v2 offset:13024
	s_waitcnt lgkmcnt(2)
	v_mfma_f32_32x32x16_bf16 v[82:97], v[14:17], v[146:149], v[82:97]
	s_mov_b64 exec, s[14:15]
	global_load_dwordx4 v[178:181], v[242:243], off
	s_mov_b64 exec, -1
	ds_read_b128 v[6:9], v2 offset:256
	s_waitcnt lgkmcnt(2)
	v_mfma_f32_32x32x16_bf16 v[98:113], v[10:13], v[150:153], v[98:113]
	ds_read_b128 v[14:17], v2 offset:13056
	s_waitcnt lgkmcnt(2)
	v_mfma_f32_32x32x16_bf16 v[82:97], v[230:233], v[150:153], v[82:97]
	ds_read_b128 v[10:13], v2 offset:288
	s_waitcnt lgkmcnt(2)
	v_mfma_f32_32x32x16_bf16 v[98:113], v[6:9], v[154:157], v[98:113]
	ds_read_b128 v[230:233], v2 offset:13088
	s_waitcnt lgkmcnt(2)
	v_mfma_f32_32x32x16_bf16 v[82:97], v[14:17], v[154:157], v[82:97]
	ds_read_b128 v[6:9], v2 offset:320
	s_waitcnt lgkmcnt(2)
	v_mfma_f32_32x32x16_bf16 v[98:113], v[10:13], v[158:161], v[98:113]
	ds_read_b128 v[14:17], v2 offset:13120
	s_waitcnt lgkmcnt(2)
	v_mfma_f32_32x32x16_bf16 v[82:97], v[230:233], v[158:161], v[82:97]
	ds_read_b128 v[10:13], v2 offset:352
	s_waitcnt lgkmcnt(2)
	v_mfma_f32_32x32x16_bf16 v[98:113], v[6:9], v[162:165], v[98:113]
	ds_read_b128 v[230:233], v2 offset:13152
	s_waitcnt lgkmcnt(2)
	v_mfma_f32_32x32x16_bf16 v[82:97], v[14:17], v[162:165], v[82:97]
	s_waitcnt lgkmcnt(1)
	v_mfma_f32_32x32x16_bf16 v[98:113], v[10:13], v[166:169], v[98:113]
	s_waitcnt lgkmcnt(0)
	v_mfma_f32_32x32x16_bf16 v[82:97], v[230:233], v[166:169], v[82:97]
	s_andn2_b64 vcc, exec, s[16:17]
	s_cbranch_vccnz .LBB0_965
; __device__ __forceinline__ void attn_item(LAS unsigned char* lds, int b, int h, int qb, const bf16_t* Q, const bf16_t* KN, const bf16_t* KR, const bf16_t* VT, bf16_t* MIXIN, float* STAT2) {
;     ...
;             if (jb >= 0) { const int qrel = 32 * w + c, kb0 = 64 * jb + 4 * hi;
; #pragma unroll
;                 for (int r = 0; r < 16; ++r) { const int kv = kb0 + (r & 3) + 8 * (r >> 2); if (kv > qrel) p0[r] = -1e30f; if (kv + 32 > qrel) p1[r] = -1e30f; } }
	v_add_u32_e32 v2, s35, v228
	v_add_u32_e32 v7, 0xfffff120, v2
	v_add_u32_e32 v6, 0xfffff100, v2
	v_cmp_le_i32_e32 vcc, v7, v227
	s_nop 5
	v_cndmask_b32_e32 v82, v226, v82, vcc
	v_cmp_lt_i32_e32 vcc, v6, v227
	s_nop 1
	v_cndmask_b32_e32 v99, v226, v99, vcc
	v_cmp_le_i32_e32 vcc, v6, v227
	v_add_u32_e32 v6, 0xfffff121, v2
	s_nop 0
	v_cndmask_b32_e32 v98, v226, v98, vcc
	v_cmp_le_i32_e32 vcc, v6, v227
	v_add_u32_e32 v6, 0xfffff102, v2
	s_nop 0
	v_cndmask_b32_e32 v83, v226, v83, vcc
	v_cmp_le_i32_e32 vcc, v6, v227
	v_add_u32_e32 v6, 0xfffff122, v2
	s_nop 0
	v_cndmask_b32_e32 v100, v226, v100, vcc
	v_cmp_le_i32_e32 vcc, v6, v227
	v_add_u32_e32 v6, 0xfffff103, v2
	s_nop 0
	v_cndmask_b32_e32 v84, v226, v84, vcc
	v_cmp_le_i32_e32 vcc, v6, v227
	v_add_u32_e32 v6, 0xfffff123, v2
	s_nop 0
	v_cndmask_b32_e32 v101, v226, v101, vcc
	v_cmp_le_i32_e32 vcc, v6, v227
	v_add_u32_e32 v6, 0xfffff108, v2
	s_nop 0
	v_cndmask_b32_e32 v85, v226, v85, vcc
	v_cmp_le_i32_e32 vcc, v6, v227
	v_add_u32_e32 v6, 0xfffff128, v2
	s_nop 0
	v_cndmask_b32_e32 v102, v226, v102, vcc
	v_cmp_le_i32_e32 vcc, v6, v227
	v_add_u32_e32 v6, 0xfffff109, v2
	s_nop 0
	v_cndmask_b32_e32 v86, v226, v86, vcc
	v_cmp_le_i32_e32 vcc, v6, v227
	v_add_u32_e32 v6, 0xfffff129, v2
	s_nop 0
	v_cndmask_b32_e32 v103, v226, v103, vcc
	v_cmp_le_i32_e32 vcc, v6, v227
	v_add_u32_e32 v6, 0xfffff10a, v2
	s_nop 0
	v_cndmask_b32_e32 v87, v226, v87, vcc
	v_cmp_le_i32_e32 vcc, v6, v227
	v_add_u32_e32 v6, 0xfffff12a, v2
	s_nop 0
	v_cndmask_b32_e32 v104, v226, v104, vcc
	v_cmp_le_i32_e32 vcc, v6, v227
	v_add_u32_e32 v6, 0xfffff10b, v2
	s_nop 0
	v_cndmask_b32_e32 v88, v226, v88, vcc
	v_cmp_le_i32_e32 vcc, v6, v227
	v_add_u32_e32 v6, 0xfffff12b, v2
	s_nop 0
	v_cndmask_b32_e32 v105, v226, v105, vcc
	v_cmp_le_i32_e32 vcc, v6, v227
	v_add_u32_e32 v6, 0xfffff110, v2
	s_nop 0
	v_cndmask_b32_e32 v89, v226, v89, vcc
	v_cmp_le_i32_e32 vcc, v6, v227
	v_add_u32_e32 v6, 0xfffff130, v2
	s_nop 0
	v_cndmask_b32_e32 v106, v226, v106, vcc
	v_cmp_le_i32_e32 vcc, v6, v227
	v_add_u32_e32 v6, 0xfffff111, v2
	s_nop 0
	v_cndmask_b32_e32 v90, v226, v90, vcc
	v_cmp_le_i32_e32 vcc, v6, v227
	v_add_u32_e32 v6, 0xfffff131, v2
	s_nop 0
	v_cndmask_b32_e32 v107, v226, v107, vcc
	v_cmp_le_i32_e32 vcc, v6, v227
	v_add_u32_e32 v6, 0xfffff112, v2
	s_nop 0
	v_cndmask_b32_e32 v91, v226, v91, vcc
	v_cmp_le_i32_e32 vcc, v6, v227
	v_add_u32_e32 v6, 0xfffff132, v2
	s_nop 0
	v_cndmask_b32_e32 v108, v226, v108, vcc
	v_cmp_le_i32_e32 vcc, v6, v227
	v_add_u32_e32 v6, 0xfffff113, v2
	s_nop 0
	v_cndmask_b32_e32 v92, v226, v92, vcc
	v_cmp_le_i32_e32 vcc, v6, v227
	v_add_u32_e32 v6, 0xfffff133, v2
	s_nop 0
	v_cndmask_b32_e32 v109, v226, v109, vcc
	v_cmp_le_i32_e32 vcc, v6, v227
	v_add_u32_e32 v6, 0xfffff118, v2
	s_nop 0
	v_cndmask_b32_e32 v93, v226, v93, vcc
	v_cmp_le_i32_e32 vcc, v6, v227
	v_add_u32_e32 v6, 0xfffff138, v2
	s_nop 0
	v_cndmask_b32_e32 v110, v226, v110, vcc
	v_cmp_le_i32_e32 vcc, v6, v227
	v_add_u32_e32 v6, 0xfffff119, v2
	s_nop 0
	v_cndmask_b32_e32 v94, v226, v94, vcc
	v_cmp_le_i32_e32 vcc, v6, v227
	v_add_u32_e32 v6, 0xfffff139, v2
	s_nop 0
	v_cndmask_b32_e32 v111, v226, v111, vcc
	v_cmp_le_i32_e32 vcc, v6, v227
	v_add_u32_e32 v6, 0xfffff11a, v2
	s_nop 0
	v_cndmask_b32_e32 v95, v226, v95, vcc
	v_cmp_le_i32_e32 vcc, v6, v227
	v_add_u32_e32 v6, 0xfffff13a, v2
	s_nop 0
	v_cndmask_b32_e32 v112, v226, v112, vcc
	v_cmp_le_i32_e32 vcc, v6, v227
	v_add_u32_e32 v6, 0xfffff11b, v2
	v_add_u32_e32 v2, 0xfffff13b, v2
	v_cndmask_b32_e32 v96, v226, v96, vcc
	v_cmp_le_i32_e32 vcc, v6, v227
	s_nop 1
	v_cndmask_b32_e32 v113, v226, v113, vcc
	v_cmp_le_i32_e32 vcc, v2, v227
	s_nop 1
	v_cndmask_b32_e32 v97, v226, v97, vcc

; __device__ __forceinline__ void attn_item(LAS unsigned char* lds, int b, int h, int qb, const bf16_t* Q, const bf16_t* KN, const bf16_t* KR, const bf16_t* VT, bf16_t* MIXIN, float* STAT2) {
;     ...
;         if (j + 1 < NT) AT_LOAD(j + 1);
;         const int jb = j - (NT - 4);
;         if (!(jb >= 0 && 64 * jb > 32 * w + 31)) {
.Latt_skipld:
	s_mov_b64 exec, s[14:15]
	global_load_dwordx4 v[138:141], v[234:235], off
	global_load_dwordx4 v[122:125], v[236:237], off
	global_load_dwordx4 v[170:173], v[238:239], off
	global_load_dwordx4 v[174:177], v[240:241], off
	global_load_dwordx4 v[178:181], v[242:243], off
	s_mov_b64 exec, -1
	s_branch .LBB0_968
